# differential-attention unit epilogues (layers 0 and 3) hand-written: loads hoisted, 16-byte gate loads and output stores via v_permlane32_swap pairs (8 instead of 16 store instructions per lane)
# baseline (speedup 1.0000x reference)
; #define GAS __attribute__((address_space(1)))
; __device__ __forceinline__ unsigned cvtpk(float lo, float hi) { typedef __bf16 b2 __attribute__((ext_vector_type(2))); f32x2 v = {lo, hi}; b2 b = __builtin_convertvector(v, b2); return __builtin_bit_cast(unsigned, b); }
;     ...
;         if (map == 0 && active) {
;             float ss = 0.f;
; #pragma unroll
;             for (int d = 0; d < 4; ++d)
; #pragma unroll
;                 for (int r = 0; r < 16; ++r) { const float v = o[d][r] * inv - xch[(sb * 64 + d * 16 + r) * 64 + lane]; o[d][r] = v; ss += v * v; }
;             ss += __shfl_xor(ss, 32);
;             const float rsn = rsqrtf(ss * (1.f / 128.f) + 1e-5f) * (1.f - lam_init);
;             const float* subg = F.a->in[14] + j * 128; const bf16* GA = (const bf16*)(F.ws + WS_GA) + (size_t)qrow * D + hcol; bf16* orow = OB + (size_t)qrow * D + hcol;
; #pragma unroll
;             for (int d = 0; d < 4; ++d)
; #pragma unroll
;                 for (int rg = 0; rg < 4; ++rg) { const int dc = d * 32 + 8 * rg + 4 * hi; const f32x4 sg = *(const GAS f32x4*)(subg + dc); const v2u gg = *(const GAS v2u*)(GA + dc);
;                     const float y0 = o[d][4 * rg + 0] * rsn * sg[0] * bf_lo(gg.x), y1 = o[d][4 * rg + 1] * rsn * sg[1] * bf_hi(gg.x), y2 = o[d][4 * rg + 2] * rsn * sg[2] * bf_lo(gg.y), y3 = o[d][4 * rg + 3] * rsn * sg[3] * bf_hi(gg.y);
;                     v2u wv; wv.x = cvtpk(y0, y1); wv.y = cvtpk(y2, y3); *(GAS v2u*)(orow + dc) = wv; }
.LBB0_567:
	s_andn2_b64 vcc, exec, s[16:17]
	s_waitcnt lgkmcnt(0)
	s_barrier
	s_cbranch_vccnz .LBB0_569
	v_lshl_add_u64 v[68:69], s[22:23], 0, v[154:155]
	s_lshl_b32 s10, s1, 1
	v_readlane_b32 s4, v254, 29
	v_lshl_add_u64 v[76:77], v[68:69], 0, s[10:11]
	v_readlane_b32 s5, v254, 30
	v_lshlrev_b32_e32 v2, 3, v166
	s_nop 0
	v_lshl_add_u64 v[68:69], s[4:5], 0, v[154:155]
	v_lshl_add_u64 v[76:77], v[76:77], 0, v[2:3]
	v_lshl_add_u64 v[70:71], v[68:69], 0, s[10:11]
	s_nop 0
	v_lshl_add_u64 v[70:71], v[70:71], 0, v[2:3]
	v_lshl_add_u64 v[76:77], v[76:77], 0, v[2:3]
	v_lshl_add_u64 v[70:71], v[70:71], 0, v[2:3]
	global_load_dwordx4 v[186:189], v[76:77], off
	global_load_dwordx4 v[190:193], v[76:77], off offset:32
	global_load_dwordx4 v[194:197], v[76:77], off offset:64
	global_load_dwordx4 v[198:201], v[76:77], off offset:96
	global_load_dwordx4 v[202:205], v[76:77], off offset:128
	global_load_dwordx4 v[206:209], v[76:77], off offset:160
	global_load_dwordx4 v[210:213], v[76:77], off offset:192
	global_load_dwordx4 v[214:217], v[76:77], off offset:224
	v_lshl_add_u32 v182, v168, 2, s59
	ds_read2st64_b32 v[84:85], v182 offset1:1
	ds_read2st64_b32 v[86:87], v182 offset0:2 offset1:3
	ds_read2st64_b32 v[88:89], v182 offset0:4 offset1:5
	ds_read2st64_b32 v[90:91], v182 offset0:6 offset1:7
	ds_read2st64_b32 v[92:93], v182 offset0:8 offset1:9
	ds_read2st64_b32 v[94:95], v182 offset0:10 offset1:11
	ds_read2st64_b32 v[96:97], v182 offset0:12 offset1:13
	ds_read2st64_b32 v[98:99], v182 offset0:14 offset1:15
	ds_read2st64_b32 v[100:101], v182 offset0:16 offset1:17
	ds_read2st64_b32 v[102:103], v182 offset0:18 offset1:19
	ds_read2st64_b32 v[104:105], v182 offset0:20 offset1:21
	ds_read2st64_b32 v[106:107], v182 offset0:22 offset1:23
	ds_read2st64_b32 v[108:109], v182 offset0:24 offset1:25
	ds_read2st64_b32 v[110:111], v182 offset0:26 offset1:27
	ds_read2st64_b32 v[112:113], v182 offset0:28 offset1:29
	ds_read2st64_b32 v[114:115], v182 offset0:30 offset1:31
	ds_read2st64_b32 v[116:117], v182 offset0:32 offset1:33
	ds_read2st64_b32 v[118:119], v182 offset0:34 offset1:35
	ds_read2st64_b32 v[120:121], v182 offset0:36 offset1:37
	ds_read2st64_b32 v[122:123], v182 offset0:38 offset1:39
	ds_read2st64_b32 v[124:125], v182 offset0:40 offset1:41
	ds_read2st64_b32 v[126:127], v182 offset0:42 offset1:43
	ds_read2st64_b32 v[128:129], v182 offset0:44 offset1:45
	ds_read2st64_b32 v[130:131], v182 offset0:46 offset1:47
	ds_read2st64_b32 v[132:133], v182 offset0:48 offset1:49
	ds_read2st64_b32 v[134:135], v182 offset0:50 offset1:51
	ds_read2st64_b32 v[136:137], v182 offset0:52 offset1:53
	ds_read2st64_b32 v[138:139], v182 offset0:54 offset1:55
	ds_read2st64_b32 v[140:141], v182 offset0:56 offset1:57
	ds_read2st64_b32 v[142:143], v182 offset0:58 offset1:59
	ds_read2st64_b32 v[144:145], v182 offset0:60 offset1:61
	ds_read2st64_b32 v[146:147], v182 offset0:62 offset1:63
	s_load_dwordx2 s[2:3], s[88:89], 0x70
	s_waitcnt lgkmcnt(0)
	v_pk_fma_f32 v[84:85], v[52:53], v[78:79], v[84:85] op_sel_hi:[1,0,1] neg_lo:[0,0,1] neg_hi:[0,0,1]
	v_pk_fma_f32 v[86:87], v[54:55], v[78:79], v[86:87] op_sel_hi:[1,0,1] neg_lo:[0,0,1] neg_hi:[0,0,1]
	v_pk_mul_f32 v[170:171], v[84:85], v[84:85]
	v_pk_mul_f32 v[172:173], v[86:87], v[86:87]
	global_load_dwordx4 v[52:55], v148, s[2:3]
	v_pk_fma_f32 v[88:89], v[56:57], v[78:79], v[88:89] op_sel_hi:[1,0,1] neg_lo:[0,0,1] neg_hi:[0,0,1]
	v_pk_fma_f32 v[90:91], v[58:59], v[78:79], v[90:91] op_sel_hi:[1,0,1] neg_lo:[0,0,1] neg_hi:[0,0,1]
	v_pk_mul_f32 v[174:175], v[88:89], v[88:89]
	v_pk_mul_f32 v[176:177], v[90:91], v[90:91]
	global_load_dwordx4 v[56:59], v148, s[2:3] offset:32
	v_pk_fma_f32 v[92:93], v[60:61], v[78:79], v[92:93] op_sel_hi:[1,0,1] neg_lo:[0,0,1] neg_hi:[0,0,1]
	v_pk_fma_f32 v[94:95], v[62:63], v[78:79], v[94:95] op_sel_hi:[1,0,1] neg_lo:[0,0,1] neg_hi:[0,0,1]
	v_pk_fma_f32 v[170:171], v[92:93], v[92:93], v[170:171]
	v_pk_fma_f32 v[172:173], v[94:95], v[94:95], v[172:173]
	global_load_dwordx4 v[60:63], v148, s[2:3] offset:64
	v_pk_fma_f32 v[96:97], v[64:65], v[78:79], v[96:97] op_sel_hi:[1,0,1] neg_lo:[0,0,1] neg_hi:[0,0,1]
	v_pk_fma_f32 v[98:99], v[66:67], v[78:79], v[98:99] op_sel_hi:[1,0,1] neg_lo:[0,0,1] neg_hi:[0,0,1]
	v_pk_fma_f32 v[174:175], v[96:97], v[96:97], v[174:175]
	v_pk_fma_f32 v[176:177], v[98:99], v[98:99], v[176:177]
	global_load_dwordx4 v[64:67], v148, s[2:3] offset:96
	v_pk_fma_f32 v[100:101], v[36:37], v[78:79], v[100:101] op_sel_hi:[1,0,1] neg_lo:[0,0,1] neg_hi:[0,0,1]
	v_pk_fma_f32 v[102:103], v[38:39], v[78:79], v[102:103] op_sel_hi:[1,0,1] neg_lo:[0,0,1] neg_hi:[0,0,1]
	v_pk_fma_f32 v[170:171], v[100:101], v[100:101], v[170:171]
	v_pk_fma_f32 v[172:173], v[102:103], v[102:103], v[172:173]
	global_load_dwordx4 v[36:39], v148, s[2:3] offset:128
	v_pk_fma_f32 v[104:105], v[40:41], v[78:79], v[104:105] op_sel_hi:[1,0,1] neg_lo:[0,0,1] neg_hi:[0,0,1]
	v_pk_fma_f32 v[106:107], v[42:43], v[78:79], v[106:107] op_sel_hi:[1,0,1] neg_lo:[0,0,1] neg_hi:[0,0,1]
	v_pk_fma_f32 v[174:175], v[104:105], v[104:105], v[174:175]
	v_pk_fma_f32 v[176:177], v[106:107], v[106:107], v[176:177]
	global_load_dwordx4 v[40:43], v148, s[2:3] offset:160
	v_pk_fma_f32 v[108:109], v[44:45], v[78:79], v[108:109] op_sel_hi:[1,0,1] neg_lo:[0,0,1] neg_hi:[0,0,1]
	v_pk_fma_f32 v[110:111], v[46:47], v[78:79], v[110:111] op_sel_hi:[1,0,1] neg_lo:[0,0,1] neg_hi:[0,0,1]
	v_pk_fma_f32 v[170:171], v[108:109], v[108:109], v[170:171]
	v_pk_fma_f32 v[172:173], v[110:111], v[110:111], v[172:173]
	global_load_dwordx4 v[44:47], v148, s[2:3] offset:192
	v_pk_fma_f32 v[112:113], v[48:49], v[78:79], v[112:113] op_sel_hi:[1,0,1] neg_lo:[0,0,1] neg_hi:[0,0,1]
; #define GAS __attribute__((address_space(1)))
; __device__ __forceinline__ unsigned cvtpk(float lo, float hi) { typedef __bf16 b2 __attribute__((ext_vector_type(2))); f32x2 v = {lo, hi}; b2 b = __builtin_convertvector(v, b2); return __builtin_bit_cast(unsigned, b); }
;     ...
;             float ss = 0.f;
; #pragma unroll
;             for (int d = 0; d < 4; ++d)
; #pragma unroll
;                 for (int r = 0; r < 16; ++r) { const float v = o[d][r] * inv - xch[(sb * 64 + d * 16 + r) * 64 + lane]; o[d][r] = v; ss += v * v; }
;             ss += __shfl_xor(ss, 32);
;             const float rsn = rsqrtf(ss * (1.f / 128.f) + 1e-5f) * (1.f - lam_init);
;             const float* subg = F.a->in[14] + j * 128; const bf16* GA = (const bf16*)(F.ws + WS_GA) + (size_t)qrow * D + hcol; bf16* orow = OB + (size_t)qrow * D + hcol;
; #pragma unroll
;             for (int d = 0; d < 4; ++d)
; #pragma unroll
;                 for (int rg = 0; rg < 4; ++rg) { const int dc = d * 32 + 8 * rg + 4 * hi; const f32x4 sg = *(const GAS f32x4*)(subg + dc); const v2u gg = *(const GAS v2u*)(GA + dc);
;                     const float y0 = o[d][4 * rg + 0] * rsn * sg[0] * bf_lo(gg.x), y1 = o[d][4 * rg + 1] * rsn * sg[1] * bf_hi(gg.x), y2 = o[d][4 * rg + 2] * rsn * sg[2] * bf_lo(gg.y), y3 = o[d][4 * rg + 3] * rsn * sg[3] * bf_hi(gg.y);
;                     v2u wv; wv.x = cvtpk(y0, y1); wv.y = cvtpk(y2, y3); *(GAS v2u*)(orow + dc) = wv; }
	v_pk_fma_f32 v[114:115], v[50:51], v[78:79], v[114:115] op_sel_hi:[1,0,1] neg_lo:[0,0,1] neg_hi:[0,0,1]
	v_pk_fma_f32 v[174:175], v[112:113], v[112:113], v[174:175]
	v_pk_fma_f32 v[176:177], v[114:115], v[114:115], v[176:177]
	global_load_dwordx4 v[48:51], v148, s[2:3] offset:224
	v_pk_fma_f32 v[116:117], v[20:21], v[78:79], v[116:117] op_sel_hi:[1,0,1] neg_lo:[0,0,1] neg_hi:[0,0,1]
	v_pk_fma_f32 v[118:119], v[22:23], v[78:79], v[118:119] op_sel_hi:[1,0,1] neg_lo:[0,0,1] neg_hi:[0,0,1]
	v_pk_fma_f32 v[170:171], v[116:117], v[116:117], v[170:171]
	v_pk_fma_f32 v[172:173], v[118:119], v[118:119], v[172:173]
	global_load_dwordx4 v[20:23], v148, s[2:3] offset:256
	v_pk_fma_f32 v[120:121], v[24:25], v[78:79], v[120:121] op_sel_hi:[1,0,1] neg_lo:[0,0,1] neg_hi:[0,0,1]
	v_pk_fma_f32 v[122:123], v[26:27], v[78:79], v[122:123] op_sel_hi:[1,0,1] neg_lo:[0,0,1] neg_hi:[0,0,1]
	v_pk_fma_f32 v[174:175], v[120:121], v[120:121], v[174:175]
	v_pk_fma_f32 v[176:177], v[122:123], v[122:123], v[176:177]
	global_load_dwordx4 v[24:27], v148, s[2:3] offset:288
	v_pk_fma_f32 v[124:125], v[28:29], v[78:79], v[124:125] op_sel_hi:[1,0,1] neg_lo:[0,0,1] neg_hi:[0,0,1]
	v_pk_fma_f32 v[126:127], v[30:31], v[78:79], v[126:127] op_sel_hi:[1,0,1] neg_lo:[0,0,1] neg_hi:[0,0,1]
	v_pk_fma_f32 v[170:171], v[124:125], v[124:125], v[170:171]
	v_pk_fma_f32 v[172:173], v[126:127], v[126:127], v[172:173]
	global_load_dwordx4 v[28:31], v148, s[2:3] offset:320
	v_pk_fma_f32 v[128:129], v[32:33], v[78:79], v[128:129] op_sel_hi:[1,0,1] neg_lo:[0,0,1] neg_hi:[0,0,1]
	v_pk_fma_f32 v[130:131], v[34:35], v[78:79], v[130:131] op_sel_hi:[1,0,1] neg_lo:[0,0,1] neg_hi:[0,0,1]
	v_pk_fma_f32 v[174:175], v[128:129], v[128:129], v[174:175]
	v_pk_fma_f32 v[176:177], v[130:131], v[130:131], v[176:177]
	global_load_dwordx4 v[32:35], v148, s[2:3] offset:352
	v_pk_fma_f32 v[132:133], v[4:5], v[78:79], v[132:133] op_sel_hi:[1,0,1] neg_lo:[0,0,1] neg_hi:[0,0,1]
	v_pk_fma_f32 v[134:135], v[6:7], v[78:79], v[134:135] op_sel_hi:[1,0,1] neg_lo:[0,0,1] neg_hi:[0,0,1]
	v_pk_fma_f32 v[170:171], v[132:133], v[132:133], v[170:171]
	v_pk_fma_f32 v[172:173], v[134:135], v[134:135], v[172:173]
	global_load_dwordx4 v[4:7], v148, s[2:3] offset:384
	v_pk_fma_f32 v[136:137], v[8:9], v[78:79], v[136:137] op_sel_hi:[1,0,1] neg_lo:[0,0,1] neg_hi:[0,0,1]
	v_pk_fma_f32 v[138:139], v[10:11], v[78:79], v[138:139] op_sel_hi:[1,0,1] neg_lo:[0,0,1] neg_hi:[0,0,1]
	v_pk_fma_f32 v[174:175], v[136:137], v[136:137], v[174:175]
	v_pk_fma_f32 v[176:177], v[138:139], v[138:139], v[176:177]
	global_load_dwordx4 v[8:11], v148, s[2:3] offset:416
	v_pk_fma_f32 v[140:141], v[12:13], v[78:79], v[140:141] op_sel_hi:[1,0,1] neg_lo:[0,0,1] neg_hi:[0,0,1]
	v_pk_fma_f32 v[142:143], v[14:15], v[78:79], v[142:143] op_sel_hi:[1,0,1] neg_lo:[0,0,1] neg_hi:[0,0,1]
	v_pk_fma_f32 v[170:171], v[140:141], v[140:141], v[170:171]
	v_pk_fma_f32 v[172:173], v[142:143], v[142:143], v[172:173]
	global_load_dwordx4 v[12:15], v148, s[2:3] offset:448
	v_pk_fma_f32 v[144:145], v[16:17], v[78:79], v[144:145] op_sel_hi:[1,0,1] neg_lo:[0,0,1] neg_hi:[0,0,1]
	v_pk_fma_f32 v[146:147], v[18:19], v[78:79], v[146:147] op_sel_hi:[1,0,1] neg_lo:[0,0,1] neg_hi:[0,0,1]
	v_pk_fma_f32 v[174:175], v[144:145], v[144:145], v[174:175]
	v_pk_fma_f32 v[176:177], v[146:147], v[146:147], v[176:177]
	global_load_dwordx4 v[16:19], v148, s[2:3] offset:480
	v_pk_add_f32 v[170:171], v[170:171], v[172:173]
	v_pk_add_f32 v[174:175], v[174:175], v[176:177]
	s_nop 0
	v_pk_add_f32 v[170:171], v[170:171], v[174:175]
	s_nop 0
	v_add_f32_e32 v178, v170, v171
	s_mov_b32 s4, 0x800000
	ds_bpermute_b32 v179, v169, v178
	s_waitcnt lgkmcnt(0)
	v_add_f32_e32 v178, v178, v179
	v_fmamk_f32 v178, v178, 0x3c000000, v165
	v_mul_f32_e32 v179, 0x4b800000, v178
	v_cmp_gt_f32_e32 vcc, s4, v178
	s_nop 1
	v_cndmask_b32_e32 v178, v178, v179, vcc
	v_rsq_f32_e32 v179, v178
	s_nop 1
	v_mul_f32_e32 v180, 0x45800000, v179
	v_cndmask_b32_e32 v180, v179, v180, vcc
	v_mul_f32_e32 v180, 0x3f4ccccd, v180
	s_waitcnt vmcnt(14)
	v_permlane32_swap_b32_e32 v186, v188
	v_permlane32_swap_b32_e32 v187, v189
	v_lshlrev_b32_e32 v154, 16, v186
	v_and_b32_e32 v155, 0xffff0000, v186
	v_lshlrev_b32_e32 v156, 16, v187
	v_and_b32_e32 v157, 0xffff0000, v187
	v_pk_mul_f32 v[84:85], v[84:85], v[180:181] op_sel_hi:[1,0]
	v_pk_mul_f32 v[86:87], v[86:87], v[180:181] op_sel_hi:[1,0]
	v_pk_mul_f32 v[84:85], v[52:53], v[84:85]
	v_pk_mul_f32 v[86:87], v[54:55], v[86:87]
	v_pk_mul_f32 v[84:85], v[84:85], v[154:155]
	v_pk_mul_f32 v[86:87], v[86:87], v[156:157]
	v_lshlrev_b32_e32 v158, 16, v188
	v_and_b32_e32 v159, 0xffff0000, v188
	v_lshlrev_b32_e32 v160, 16, v189
	v_and_b32_e32 v161, 0xffff0000, v189
	v_pk_mul_f32 v[88:89], v[88:89], v[180:181] op_sel_hi:[1,0]
	v_pk_mul_f32 v[90:91], v[90:91], v[180:181] op_sel_hi:[1,0]
	v_pk_mul_f32 v[88:89], v[56:57], v[88:89]
	v_pk_mul_f32 v[90:91], v[58:59], v[90:91]
	v_pk_mul_f32 v[88:89], v[88:89], v[158:159]
	v_pk_mul_f32 v[90:91], v[90:91], v[160:161]
	v_cvt_pk_bf16_f32 v84, v84, v85
	v_cvt_pk_bf16_f32 v85, v86, v87
	v_cvt_pk_bf16_f32 v86, v88, v89
	v_cvt_pk_bf16_f32 v87, v90, v91
	s_nop 1
	v_permlane32_swap_b32_e32 v84, v86
	v_permlane32_swap_b32_e32 v85, v87
	global_store_dwordx4 v[70:71], v[84:87], off
	s_waitcnt vmcnt(13)
; #define GAS __attribute__((address_space(1)))
; __device__ __forceinline__ unsigned cvtpk(float lo, float hi) { typedef __bf16 b2 __attribute__((ext_vector_type(2))); f32x2 v = {lo, hi}; b2 b = __builtin_convertvector(v, b2); return __builtin_bit_cast(unsigned, b); }
;     ...
;             for (int d = 0; d < 4; ++d)
; #pragma unroll
;                 for (int rg = 0; rg < 4; ++rg) { const int dc = d * 32 + 8 * rg + 4 * hi; const f32x4 sg = *(const GAS f32x4*)(subg + dc); const v2u gg = *(const GAS v2u*)(GA + dc);
;                     const float y0 = o[d][4 * rg + 0] * rsn * sg[0] * bf_lo(gg.x), y1 = o[d][4 * rg + 1] * rsn * sg[1] * bf_hi(gg.x), y2 = o[d][4 * rg + 2] * rsn * sg[2] * bf_lo(gg.y), y3 = o[d][4 * rg + 3] * rsn * sg[3] * bf_hi(gg.y);
;                     v2u wv; wv.x = cvtpk(y0, y1); wv.y = cvtpk(y2, y3); *(GAS v2u*)(orow + dc) = wv; }
	v_permlane32_swap_b32_e32 v190, v192
	v_permlane32_swap_b32_e32 v191, v193
	v_lshlrev_b32_e32 v154, 16, v190
	v_and_b32_e32 v155, 0xffff0000, v190
	v_lshlrev_b32_e32 v156, 16, v191
	v_and_b32_e32 v157, 0xffff0000, v191
	v_pk_mul_f32 v[92:93], v[92:93], v[180:181] op_sel_hi:[1,0]
	v_pk_mul_f32 v[94:95], v[94:95], v[180:181] op_sel_hi:[1,0]
	v_pk_mul_f32 v[92:93], v[60:61], v[92:93]
	v_pk_mul_f32 v[94:95], v[62:63], v[94:95]
	v_pk_mul_f32 v[92:93], v[92:93], v[154:155]
	v_pk_mul_f32 v[94:95], v[94:95], v[156:157]
	v_lshlrev_b32_e32 v158, 16, v192
	v_and_b32_e32 v159, 0xffff0000, v192
	v_lshlrev_b32_e32 v160, 16, v193
	v_and_b32_e32 v161, 0xffff0000, v193
	v_pk_mul_f32 v[96:97], v[96:97], v[180:181] op_sel_hi:[1,0]
	v_pk_mul_f32 v[98:99], v[98:99], v[180:181] op_sel_hi:[1,0]
	v_pk_mul_f32 v[96:97], v[64:65], v[96:97]
	v_pk_mul_f32 v[98:99], v[66:67], v[98:99]
	v_pk_mul_f32 v[96:97], v[96:97], v[158:159]
	v_pk_mul_f32 v[98:99], v[98:99], v[160:161]
	v_cvt_pk_bf16_f32 v92, v92, v93
	v_cvt_pk_bf16_f32 v93, v94, v95
	v_cvt_pk_bf16_f32 v94, v96, v97
	v_cvt_pk_bf16_f32 v95, v98, v99
	s_nop 1
	v_permlane32_swap_b32_e32 v92, v94
	v_permlane32_swap_b32_e32 v93, v95
	global_store_dwordx4 v[70:71], v[92:95], off offset:32
	s_waitcnt vmcnt(12)
	v_permlane32_swap_b32_e32 v194, v196
	v_permlane32_swap_b32_e32 v195, v197
	v_lshlrev_b32_e32 v154, 16, v194
	v_and_b32_e32 v155, 0xffff0000, v194
	v_lshlrev_b32_e32 v156, 16, v195
	v_and_b32_e32 v157, 0xffff0000, v195
	v_pk_mul_f32 v[100:101], v[100:101], v[180:181] op_sel_hi:[1,0]
	v_pk_mul_f32 v[102:103], v[102:103], v[180:181] op_sel_hi:[1,0]
	v_pk_mul_f32 v[100:101], v[36:37], v[100:101]
	v_pk_mul_f32 v[102:103], v[38:39], v[102:103]
	v_pk_mul_f32 v[100:101], v[100:101], v[154:155]
	v_pk_mul_f32 v[102:103], v[102:103], v[156:157]
	v_lshlrev_b32_e32 v158, 16, v196
	v_and_b32_e32 v159, 0xffff0000, v196
	v_lshlrev_b32_e32 v160, 16, v197
	v_and_b32_e32 v161, 0xffff0000, v197
	v_pk_mul_f32 v[104:105], v[104:105], v[180:181] op_sel_hi:[1,0]
	v_pk_mul_f32 v[106:107], v[106:107], v[180:181] op_sel_hi:[1,0]
	v_pk_mul_f32 v[104:105], v[40:41], v[104:105]
	v_pk_mul_f32 v[106:107], v[42:43], v[106:107]
	v_pk_mul_f32 v[104:105], v[104:105], v[158:159]
	v_pk_mul_f32 v[106:107], v[106:107], v[160:161]
	v_cvt_pk_bf16_f32 v100, v100, v101
	v_cvt_pk_bf16_f32 v101, v102, v103
	v_cvt_pk_bf16_f32 v102, v104, v105
	v_cvt_pk_bf16_f32 v103, v106, v107
	s_nop 1
	v_permlane32_swap_b32_e32 v100, v102
	v_permlane32_swap_b32_e32 v101, v103
	global_store_dwordx4 v[70:71], v[100:103], off offset:64
	s_waitcnt vmcnt(11)
	v_permlane32_swap_b32_e32 v198, v200
	v_permlane32_swap_b32_e32 v199, v201
	v_lshlrev_b32_e32 v154, 16, v198
	v_and_b32_e32 v155, 0xffff0000, v198
	v_lshlrev_b32_e32 v156, 16, v199
	v_and_b32_e32 v157, 0xffff0000, v199
	v_pk_mul_f32 v[108:109], v[108:109], v[180:181] op_sel_hi:[1,0]
	v_pk_mul_f32 v[110:111], v[110:111], v[180:181] op_sel_hi:[1,0]
	v_pk_mul_f32 v[108:109], v[44:45], v[108:109]
	v_pk_mul_f32 v[110:111], v[46:47], v[110:111]
	v_pk_mul_f32 v[108:109], v[108:109], v[154:155]
	v_pk_mul_f32 v[110:111], v[110:111], v[156:157]
	v_lshlrev_b32_e32 v158, 16, v200
	v_and_b32_e32 v159, 0xffff0000, v200
	v_lshlrev_b32_e32 v160, 16, v201
	v_and_b32_e32 v161, 0xffff0000, v201
	v_pk_mul_f32 v[112:113], v[112:113], v[180:181] op_sel_hi:[1,0]
	v_pk_mul_f32 v[114:115], v[114:115], v[180:181] op_sel_hi:[1,0]
	v_pk_mul_f32 v[112:113], v[48:49], v[112:113]
	v_pk_mul_f32 v[114:115], v[50:51], v[114:115]
	v_pk_mul_f32 v[112:113], v[112:113], v[158:159]
	v_pk_mul_f32 v[114:115], v[114:115], v[160:161]
	v_cvt_pk_bf16_f32 v108, v108, v109
	v_cvt_pk_bf16_f32 v109, v110, v111
	v_cvt_pk_bf16_f32 v110, v112, v113
	v_cvt_pk_bf16_f32 v111, v114, v115
	s_nop 1
	v_permlane32_swap_b32_e32 v108, v110
	v_permlane32_swap_b32_e32 v109, v111
	global_store_dwordx4 v[70:71], v[108:111], off offset:96
	s_waitcnt vmcnt(10)
	v_permlane32_swap_b32_e32 v202, v204
	v_permlane32_swap_b32_e32 v203, v205
	v_lshlrev_b32_e32 v154, 16, v202
	v_and_b32_e32 v155, 0xffff0000, v202
	v_lshlrev_b32_e32 v156, 16, v203
	v_and_b32_e32 v157, 0xffff0000, v203
	v_pk_mul_f32 v[116:117], v[116:117], v[180:181] op_sel_hi:[1,0]
	v_pk_mul_f32 v[118:119], v[118:119], v[180:181] op_sel_hi:[1,0]
	v_pk_mul_f32 v[116:117], v[20:21], v[116:117]
	v_pk_mul_f32 v[118:119], v[22:23], v[118:119]
	v_pk_mul_f32 v[116:117], v[116:117], v[154:155]
	v_pk_mul_f32 v[118:119], v[118:119], v[156:157]
	v_lshlrev_b32_e32 v158, 16, v204
	v_and_b32_e32 v159, 0xffff0000, v204
	v_lshlrev_b32_e32 v160, 16, v205
	v_and_b32_e32 v161, 0xffff0000, v205
	v_pk_mul_f32 v[120:121], v[120:121], v[180:181] op_sel_hi:[1,0]
	v_pk_mul_f32 v[122:123], v[122:123], v[180:181] op_sel_hi:[1,0]
	v_pk_mul_f32 v[120:121], v[24:25], v[120:121]
	v_pk_mul_f32 v[122:123], v[26:27], v[122:123]
	v_pk_mul_f32 v[120:121], v[120:121], v[158:159]
	v_pk_mul_f32 v[122:123], v[122:123], v[160:161]
	v_cvt_pk_bf16_f32 v116, v116, v117
	v_cvt_pk_bf16_f32 v117, v118, v119
	v_cvt_pk_bf16_f32 v118, v120, v121
	v_cvt_pk_bf16_f32 v119, v122, v123
	s_nop 1
	v_permlane32_swap_b32_e32 v116, v118
	v_permlane32_swap_b32_e32 v117, v119
	global_store_dwordx4 v[70:71], v[116:119], off offset:128
	s_waitcnt vmcnt(9)
; #define GAS __attribute__((address_space(1)))
; __device__ __forceinline__ unsigned cvtpk(float lo, float hi) { typedef __bf16 b2 __attribute__((ext_vector_type(2))); f32x2 v = {lo, hi}; b2 b = __builtin_convertvector(v, b2); return __builtin_bit_cast(unsigned, b); }
;     ...
;             for (int d = 0; d < 4; ++d)
; #pragma unroll
;                 for (int rg = 0; rg < 4; ++rg) { const int dc = d * 32 + 8 * rg + 4 * hi; const f32x4 sg = *(const GAS f32x4*)(subg + dc); const v2u gg = *(const GAS v2u*)(GA + dc);
;                     const float y0 = o[d][4 * rg + 0] * rsn * sg[0] * bf_lo(gg.x), y1 = o[d][4 * rg + 1] * rsn * sg[1] * bf_hi(gg.x), y2 = o[d][4 * rg + 2] * rsn * sg[2] * bf_lo(gg.y), y3 = o[d][4 * rg + 3] * rsn * sg[3] * bf_hi(gg.y);
;                     v2u wv; wv.x = cvtpk(y0, y1); wv.y = cvtpk(y2, y3); *(GAS v2u*)(orow + dc) = wv; }
	v_permlane32_swap_b32_e32 v206, v208
	v_permlane32_swap_b32_e32 v207, v209
	v_lshlrev_b32_e32 v154, 16, v206
	v_and_b32_e32 v155, 0xffff0000, v206
	v_lshlrev_b32_e32 v156, 16, v207
	v_and_b32_e32 v157, 0xffff0000, v207
	v_pk_mul_f32 v[124:125], v[124:125], v[180:181] op_sel_hi:[1,0]
	v_pk_mul_f32 v[126:127], v[126:127], v[180:181] op_sel_hi:[1,0]
	v_pk_mul_f32 v[124:125], v[28:29], v[124:125]
	v_pk_mul_f32 v[126:127], v[30:31], v[126:127]
	v_pk_mul_f32 v[124:125], v[124:125], v[154:155]
	v_pk_mul_f32 v[126:127], v[126:127], v[156:157]
	v_lshlrev_b32_e32 v158, 16, v208
	v_and_b32_e32 v159, 0xffff0000, v208
	v_lshlrev_b32_e32 v160, 16, v209
	v_and_b32_e32 v161, 0xffff0000, v209
	v_pk_mul_f32 v[128:129], v[128:129], v[180:181] op_sel_hi:[1,0]
	v_pk_mul_f32 v[130:131], v[130:131], v[180:181] op_sel_hi:[1,0]
	v_pk_mul_f32 v[128:129], v[32:33], v[128:129]
	v_pk_mul_f32 v[130:131], v[34:35], v[130:131]
	v_pk_mul_f32 v[128:129], v[128:129], v[158:159]
	v_pk_mul_f32 v[130:131], v[130:131], v[160:161]
	v_cvt_pk_bf16_f32 v124, v124, v125
	v_cvt_pk_bf16_f32 v125, v126, v127
	v_cvt_pk_bf16_f32 v126, v128, v129
	v_cvt_pk_bf16_f32 v127, v130, v131
	s_nop 1
	v_permlane32_swap_b32_e32 v124, v126
	v_permlane32_swap_b32_e32 v125, v127
	global_store_dwordx4 v[70:71], v[124:127], off offset:160
	s_waitcnt vmcnt(8)
	v_permlane32_swap_b32_e32 v210, v212
	v_permlane32_swap_b32_e32 v211, v213
	v_lshlrev_b32_e32 v154, 16, v210
	v_and_b32_e32 v155, 0xffff0000, v210
	v_lshlrev_b32_e32 v156, 16, v211
	v_and_b32_e32 v157, 0xffff0000, v211
	v_pk_mul_f32 v[132:133], v[132:133], v[180:181] op_sel_hi:[1,0]
	v_pk_mul_f32 v[134:135], v[134:135], v[180:181] op_sel_hi:[1,0]
	v_pk_mul_f32 v[132:133], v[4:5], v[132:133]
	v_pk_mul_f32 v[134:135], v[6:7], v[134:135]
	v_pk_mul_f32 v[132:133], v[132:133], v[154:155]
	v_pk_mul_f32 v[134:135], v[134:135], v[156:157]
	v_lshlrev_b32_e32 v158, 16, v212
	v_and_b32_e32 v159, 0xffff0000, v212
	v_lshlrev_b32_e32 v160, 16, v213
	v_and_b32_e32 v161, 0xffff0000, v213
	v_pk_mul_f32 v[136:137], v[136:137], v[180:181] op_sel_hi:[1,0]
	v_pk_mul_f32 v[138:139], v[138:139], v[180:181] op_sel_hi:[1,0]
	v_pk_mul_f32 v[136:137], v[8:9], v[136:137]
	v_pk_mul_f32 v[138:139], v[10:11], v[138:139]
	v_pk_mul_f32 v[136:137], v[136:137], v[158:159]
	v_pk_mul_f32 v[138:139], v[138:139], v[160:161]
	v_cvt_pk_bf16_f32 v132, v132, v133
	v_cvt_pk_bf16_f32 v133, v134, v135
	v_cvt_pk_bf16_f32 v134, v136, v137
	v_cvt_pk_bf16_f32 v135, v138, v139
	s_nop 1
	v_permlane32_swap_b32_e32 v132, v134
	v_permlane32_swap_b32_e32 v133, v135
	global_store_dwordx4 v[70:71], v[132:135], off offset:192
	s_waitcnt vmcnt(7)
	v_permlane32_swap_b32_e32 v214, v216
	v_permlane32_swap_b32_e32 v215, v217
	v_lshlrev_b32_e32 v154, 16, v214
	v_and_b32_e32 v155, 0xffff0000, v214
	v_lshlrev_b32_e32 v156, 16, v215
	v_and_b32_e32 v157, 0xffff0000, v215
	v_pk_mul_f32 v[140:141], v[140:141], v[180:181] op_sel_hi:[1,0]
	v_pk_mul_f32 v[142:143], v[142:143], v[180:181] op_sel_hi:[1,0]
	v_pk_mul_f32 v[140:141], v[12:13], v[140:141]
	v_pk_mul_f32 v[142:143], v[14:15], v[142:143]
	v_pk_mul_f32 v[140:141], v[140:141], v[154:155]
	v_pk_mul_f32 v[142:143], v[142:143], v[156:157]
	v_lshlrev_b32_e32 v158, 16, v216
	v_and_b32_e32 v159, 0xffff0000, v216
	v_lshlrev_b32_e32 v160, 16, v217
	v_and_b32_e32 v161, 0xffff0000, v217
	v_pk_mul_f32 v[144:145], v[144:145], v[180:181] op_sel_hi:[1,0]
	v_pk_mul_f32 v[146:147], v[146:147], v[180:181] op_sel_hi:[1,0]
	v_pk_mul_f32 v[144:145], v[16:17], v[144:145]
	v_pk_mul_f32 v[146:147], v[18:19], v[146:147]
	v_pk_mul_f32 v[144:145], v[144:145], v[158:159]
	v_pk_mul_f32 v[146:147], v[146:147], v[160:161]
	v_cvt_pk_bf16_f32 v140, v140, v141
	v_cvt_pk_bf16_f32 v141, v142, v143
	v_cvt_pk_bf16_f32 v142, v144, v145
	v_cvt_pk_bf16_f32 v143, v146, v147
	s_nop 1
	v_permlane32_swap_b32_e32 v140, v142
	v_permlane32_swap_b32_e32 v141, v143
	global_store_dwordx4 v[70:71], v[140:143], off offset:224

; #define GAS __attribute__((address_space(1)))
; __device__ __forceinline__ unsigned cvtpk(float lo, float hi) { typedef __bf16 b2 __attribute__((ext_vector_type(2))); f32x2 v = {lo, hi}; b2 b = __builtin_convertvector(v, b2); return __builtin_bit_cast(unsigned, b); }
;     ...
;         if (map == 0 && active) {
;             float ss = 0.f;
; #pragma unroll
;             for (int d = 0; d < 4; ++d)
; #pragma unroll
;                 for (int r = 0; r < 16; ++r) { const float v = o[d][r] * inv - xch[(sb * 64 + d * 16 + r) * 64 + lane]; o[d][r] = v; ss += v * v; }
;             ss += __shfl_xor(ss, 32);
;             const float rsn = rsqrtf(ss * (1.f / 128.f) + 1e-5f) * (1.f - lam_init);
;             const float* subg = F.a->in[14] + j * 128; const bf16* GA = (const bf16*)(F.ws + WS_GA) + (size_t)qrow * D + hcol; bf16* orow = OB + (size_t)qrow * D + hcol;
; #pragma unroll
;             for (int d = 0; d < 4; ++d)
; #pragma unroll
;                 for (int rg = 0; rg < 4; ++rg) { const int dc = d * 32 + 8 * rg + 4 * hi; const f32x4 sg = *(const GAS f32x4*)(subg + dc); const v2u gg = *(const GAS v2u*)(GA + dc);
;                     const float y0 = o[d][4 * rg + 0] * rsn * sg[0] * bf_lo(gg.x), y1 = o[d][4 * rg + 1] * rsn * sg[1] * bf_hi(gg.x), y2 = o[d][4 * rg + 2] * rsn * sg[2] * bf_lo(gg.y), y3 = o[d][4 * rg + 3] * rsn * sg[3] * bf_hi(gg.y);
;                     v2u wv; wv.x = cvtpk(y0, y1); wv.y = cvtpk(y2, y3); *(GAS v2u*)(orow + dc) = wv; }
.LBB0_3334:
	s_andn2_b64 vcc, exec, s[10:11]
	s_waitcnt vmcnt(0) lgkmcnt(0)
	s_barrier
	s_cbranch_vccnz .LBB0_3336
	v_lshl_add_u64 v[72:73], s[18:19], 0, v[172:173]
	s_lshl_b32 s6, s4, 1
	v_readlane_b32 s4, v254, 29
	v_lshl_add_u64 v[74:75], v[72:73], 0, s[6:7]
	v_readlane_b32 s5, v254, 30
	v_lshlrev_b32_e32 v162, 3, v187
	v_readlane_b32 s2, v254, 27
	v_lshl_add_u64 v[72:73], s[4:5], 0, v[172:173]
	v_lshl_add_u64 v[74:75], v[74:75], 0, v[162:163]
	v_readlane_b32 s3, v254, 28
	v_lshl_add_u64 v[88:89], v[72:73], 0, s[6:7]
	s_nop 0
	v_lshl_add_u64 v[88:89], v[88:89], 0, v[162:163]
	v_lshl_add_u64 v[74:75], v[74:75], 0, v[162:163]
	v_lshl_add_u64 v[88:89], v[88:89], 0, v[162:163]
	global_load_dwordx4 v[188:191], v[74:75], off
	global_load_dwordx4 v[192:195], v[74:75], off offset:32
	global_load_dwordx4 v[196:199], v[74:75], off offset:64
	global_load_dwordx4 v[200:203], v[74:75], off offset:96
	global_load_dwordx4 v[204:207], v[74:75], off offset:128
	global_load_dwordx4 v[208:211], v[74:75], off offset:160
	global_load_dwordx4 v[212:215], v[74:75], off offset:192
	global_load_dwordx4 v[216:219], v[74:75], off offset:224
	v_lshl_add_u32 v70, v186, 2, s73
	ds_read2st64_b32 v[92:93], v70 offset1:1
	ds_read2st64_b32 v[94:95], v70 offset0:2 offset1:3
	ds_read2st64_b32 v[96:97], v70 offset0:4 offset1:5
	ds_read2st64_b32 v[98:99], v70 offset0:6 offset1:7
	ds_read2st64_b32 v[100:101], v70 offset0:8 offset1:9
	ds_read2st64_b32 v[102:103], v70 offset0:10 offset1:11
	ds_read2st64_b32 v[104:105], v70 offset0:12 offset1:13
	ds_read2st64_b32 v[106:107], v70 offset0:14 offset1:15
	ds_read2st64_b32 v[108:109], v70 offset0:16 offset1:17
	ds_read2st64_b32 v[110:111], v70 offset0:18 offset1:19
	ds_read2st64_b32 v[112:113], v70 offset0:20 offset1:21
	ds_read2st64_b32 v[114:115], v70 offset0:22 offset1:23
	ds_read2st64_b32 v[116:117], v70 offset0:24 offset1:25
	ds_read2st64_b32 v[118:119], v70 offset0:26 offset1:27
	ds_read2st64_b32 v[120:121], v70 offset0:28 offset1:29
	ds_read2st64_b32 v[122:123], v70 offset0:30 offset1:31
	ds_read2st64_b32 v[124:125], v70 offset0:32 offset1:33
	ds_read2st64_b32 v[126:127], v70 offset0:34 offset1:35
	ds_read2st64_b32 v[128:129], v70 offset0:36 offset1:37
	ds_read2st64_b32 v[130:131], v70 offset0:38 offset1:39
	ds_read2st64_b32 v[132:133], v70 offset0:40 offset1:41
	ds_read2st64_b32 v[134:135], v70 offset0:42 offset1:43
	ds_read2st64_b32 v[136:137], v70 offset0:44 offset1:45
	ds_read2st64_b32 v[138:139], v70 offset0:46 offset1:47
	ds_read2st64_b32 v[140:141], v70 offset0:48 offset1:49
	ds_read2st64_b32 v[142:143], v70 offset0:50 offset1:51
	ds_read2st64_b32 v[144:145], v70 offset0:52 offset1:53
	ds_read2st64_b32 v[146:147], v70 offset0:54 offset1:55
	ds_read2st64_b32 v[148:149], v70 offset0:56 offset1:57
	ds_read2st64_b32 v[150:151], v70 offset0:58 offset1:59
	ds_read2st64_b32 v[152:153], v70 offset0:60 offset1:61
	ds_read2st64_b32 v[154:155], v70 offset0:62 offset1:63
	s_load_dwordx2 s[2:3], s[2:3], 0x70
	s_waitcnt lgkmcnt(0)
	v_pk_fma_f32 v[92:93], v[50:51], v[76:77], v[92:93] op_sel_hi:[1,0,1] neg_lo:[0,0,1] neg_hi:[0,0,1]
	v_pk_fma_f32 v[94:95], v[52:53], v[76:77], v[94:95] op_sel_hi:[1,0,1] neg_lo:[0,0,1] neg_hi:[0,0,1]
	v_pk_mul_f32 v[156:157], v[92:93], v[92:93]
	v_pk_mul_f32 v[160:161], v[94:95], v[94:95]
	global_load_dwordx4 v[50:53], v166, s[2:3] offset:512
	v_pk_fma_f32 v[96:97], v[54:55], v[76:77], v[96:97] op_sel_hi:[1,0,1] neg_lo:[0,0,1] neg_hi:[0,0,1]
	v_pk_fma_f32 v[98:99], v[56:57], v[76:77], v[98:99] op_sel_hi:[1,0,1] neg_lo:[0,0,1] neg_hi:[0,0,1]
	v_pk_mul_f32 v[174:175], v[96:97], v[96:97]
	v_pk_mul_f32 v[176:177], v[98:99], v[98:99]
	global_load_dwordx4 v[54:57], v166, s[2:3] offset:544
	v_pk_fma_f32 v[100:101], v[58:59], v[76:77], v[100:101] op_sel_hi:[1,0,1] neg_lo:[0,0,1] neg_hi:[0,0,1]
	v_pk_fma_f32 v[102:103], v[60:61], v[76:77], v[102:103] op_sel_hi:[1,0,1] neg_lo:[0,0,1] neg_hi:[0,0,1]
	v_pk_fma_f32 v[156:157], v[100:101], v[100:101], v[156:157]
	v_pk_fma_f32 v[160:161], v[102:103], v[102:103], v[160:161]
	global_load_dwordx4 v[58:61], v166, s[2:3] offset:576
	v_pk_fma_f32 v[104:105], v[62:63], v[76:77], v[104:105] op_sel_hi:[1,0,1] neg_lo:[0,0,1] neg_hi:[0,0,1]
	v_pk_fma_f32 v[106:107], v[64:65], v[76:77], v[106:107] op_sel_hi:[1,0,1] neg_lo:[0,0,1] neg_hi:[0,0,1]
	v_pk_fma_f32 v[174:175], v[104:105], v[104:105], v[174:175]
	v_pk_fma_f32 v[176:177], v[106:107], v[106:107], v[176:177]
	global_load_dwordx4 v[62:65], v166, s[2:3] offset:608
	v_pk_fma_f32 v[108:109], v[34:35], v[76:77], v[108:109] op_sel_hi:[1,0,1] neg_lo:[0,0,1] neg_hi:[0,0,1]
	v_pk_fma_f32 v[110:111], v[36:37], v[76:77], v[110:111] op_sel_hi:[1,0,1] neg_lo:[0,0,1] neg_hi:[0,0,1]
	v_pk_fma_f32 v[156:157], v[108:109], v[108:109], v[156:157]
	v_pk_fma_f32 v[160:161], v[110:111], v[110:111], v[160:161]
	global_load_dwordx4 v[34:37], v166, s[2:3] offset:640
	v_pk_fma_f32 v[112:113], v[38:39], v[76:77], v[112:113] op_sel_hi:[1,0,1] neg_lo:[0,0,1] neg_hi:[0,0,1]
	v_pk_fma_f32 v[114:115], v[40:41], v[76:77], v[114:115] op_sel_hi:[1,0,1] neg_lo:[0,0,1] neg_hi:[0,0,1]
	v_pk_fma_f32 v[174:175], v[112:113], v[112:113], v[174:175]
	v_pk_fma_f32 v[176:177], v[114:115], v[114:115], v[176:177]
	global_load_dwordx4 v[38:41], v166, s[2:3] offset:672
	v_pk_fma_f32 v[116:117], v[42:43], v[76:77], v[116:117] op_sel_hi:[1,0,1] neg_lo:[0,0,1] neg_hi:[0,0,1]
	v_pk_fma_f32 v[118:119], v[44:45], v[76:77], v[118:119] op_sel_hi:[1,0,1] neg_lo:[0,0,1] neg_hi:[0,0,1]
	v_pk_fma_f32 v[156:157], v[116:117], v[116:117], v[156:157]
	v_pk_fma_f32 v[160:161], v[118:119], v[118:119], v[160:161]
	global_load_dwordx4 v[42:45], v166, s[2:3] offset:704
; #define GAS __attribute__((address_space(1)))
; __device__ __forceinline__ unsigned cvtpk(float lo, float hi) { typedef __bf16 b2 __attribute__((ext_vector_type(2))); f32x2 v = {lo, hi}; b2 b = __builtin_convertvector(v, b2); return __builtin_bit_cast(unsigned, b); }
;     ...
;             float ss = 0.f;
; #pragma unroll
;             for (int d = 0; d < 4; ++d)
; #pragma unroll
;                 for (int r = 0; r < 16; ++r) { const float v = o[d][r] * inv - xch[(sb * 64 + d * 16 + r) * 64 + lane]; o[d][r] = v; ss += v * v; }
;             ss += __shfl_xor(ss, 32);
;             const float rsn = rsqrtf(ss * (1.f / 128.f) + 1e-5f) * (1.f - lam_init);
;             const float* subg = F.a->in[14] + j * 128; const bf16* GA = (const bf16*)(F.ws + WS_GA) + (size_t)qrow * D + hcol; bf16* orow = OB + (size_t)qrow * D + hcol;
; #pragma unroll
;             for (int d = 0; d < 4; ++d)
; #pragma unroll
;                 for (int rg = 0; rg < 4; ++rg) { const int dc = d * 32 + 8 * rg + 4 * hi; const f32x4 sg = *(const GAS f32x4*)(subg + dc); const v2u gg = *(const GAS v2u*)(GA + dc);
;                     const float y0 = o[d][4 * rg + 0] * rsn * sg[0] * bf_lo(gg.x), y1 = o[d][4 * rg + 1] * rsn * sg[1] * bf_hi(gg.x), y2 = o[d][4 * rg + 2] * rsn * sg[2] * bf_lo(gg.y), y3 = o[d][4 * rg + 3] * rsn * sg[3] * bf_hi(gg.y);
;                     v2u wv; wv.x = cvtpk(y0, y1); wv.y = cvtpk(y2, y3); *(GAS v2u*)(orow + dc) = wv; }
	v_pk_fma_f32 v[120:121], v[46:47], v[76:77], v[120:121] op_sel_hi:[1,0,1] neg_lo:[0,0,1] neg_hi:[0,0,1]
	v_pk_fma_f32 v[122:123], v[48:49], v[76:77], v[122:123] op_sel_hi:[1,0,1] neg_lo:[0,0,1] neg_hi:[0,0,1]
	v_pk_fma_f32 v[174:175], v[120:121], v[120:121], v[174:175]
	v_pk_fma_f32 v[176:177], v[122:123], v[122:123], v[176:177]
	global_load_dwordx4 v[46:49], v166, s[2:3] offset:736
	v_pk_fma_f32 v[124:125], v[18:19], v[76:77], v[124:125] op_sel_hi:[1,0,1] neg_lo:[0,0,1] neg_hi:[0,0,1]
	v_pk_fma_f32 v[126:127], v[20:21], v[76:77], v[126:127] op_sel_hi:[1,0,1] neg_lo:[0,0,1] neg_hi:[0,0,1]
	v_pk_fma_f32 v[156:157], v[124:125], v[124:125], v[156:157]
	v_pk_fma_f32 v[160:161], v[126:127], v[126:127], v[160:161]
	global_load_dwordx4 v[18:21], v166, s[2:3] offset:768
	v_pk_fma_f32 v[128:129], v[22:23], v[76:77], v[128:129] op_sel_hi:[1,0,1] neg_lo:[0,0,1] neg_hi:[0,0,1]
	v_pk_fma_f32 v[130:131], v[24:25], v[76:77], v[130:131] op_sel_hi:[1,0,1] neg_lo:[0,0,1] neg_hi:[0,0,1]
	v_pk_fma_f32 v[174:175], v[128:129], v[128:129], v[174:175]
	v_pk_fma_f32 v[176:177], v[130:131], v[130:131], v[176:177]
	global_load_dwordx4 v[22:25], v166, s[2:3] offset:800
	v_pk_fma_f32 v[132:133], v[26:27], v[76:77], v[132:133] op_sel_hi:[1,0,1] neg_lo:[0,0,1] neg_hi:[0,0,1]
	v_pk_fma_f32 v[134:135], v[28:29], v[76:77], v[134:135] op_sel_hi:[1,0,1] neg_lo:[0,0,1] neg_hi:[0,0,1]
	v_pk_fma_f32 v[156:157], v[132:133], v[132:133], v[156:157]
	v_pk_fma_f32 v[160:161], v[134:135], v[134:135], v[160:161]
	global_load_dwordx4 v[26:29], v166, s[2:3] offset:832
	v_pk_fma_f32 v[136:137], v[30:31], v[76:77], v[136:137] op_sel_hi:[1,0,1] neg_lo:[0,0,1] neg_hi:[0,0,1]
	v_pk_fma_f32 v[138:139], v[32:33], v[76:77], v[138:139] op_sel_hi:[1,0,1] neg_lo:[0,0,1] neg_hi:[0,0,1]
	v_pk_fma_f32 v[174:175], v[136:137], v[136:137], v[174:175]
	v_pk_fma_f32 v[176:177], v[138:139], v[138:139], v[176:177]
	global_load_dwordx4 v[30:33], v166, s[2:3] offset:864
	v_pk_fma_f32 v[140:141], v[2:3], v[76:77], v[140:141] op_sel_hi:[1,0,1] neg_lo:[0,0,1] neg_hi:[0,0,1]
	v_pk_fma_f32 v[142:143], v[4:5], v[76:77], v[142:143] op_sel_hi:[1,0,1] neg_lo:[0,0,1] neg_hi:[0,0,1]
	v_pk_fma_f32 v[156:157], v[140:141], v[140:141], v[156:157]
	v_pk_fma_f32 v[160:161], v[142:143], v[142:143], v[160:161]
	global_load_dwordx4 v[2:5], v166, s[2:3] offset:896
	v_pk_fma_f32 v[144:145], v[6:7], v[76:77], v[144:145] op_sel_hi:[1,0,1] neg_lo:[0,0,1] neg_hi:[0,0,1]
	v_pk_fma_f32 v[146:147], v[8:9], v[76:77], v[146:147] op_sel_hi:[1,0,1] neg_lo:[0,0,1] neg_hi:[0,0,1]
	v_pk_fma_f32 v[174:175], v[144:145], v[144:145], v[174:175]
	v_pk_fma_f32 v[176:177], v[146:147], v[146:147], v[176:177]
	global_load_dwordx4 v[6:9], v166, s[2:3] offset:928
	v_pk_fma_f32 v[148:149], v[10:11], v[76:77], v[148:149] op_sel_hi:[1,0,1] neg_lo:[0,0,1] neg_hi:[0,0,1]
	v_pk_fma_f32 v[150:151], v[12:13], v[76:77], v[150:151] op_sel_hi:[1,0,1] neg_lo:[0,0,1] neg_hi:[0,0,1]
	v_pk_fma_f32 v[156:157], v[148:149], v[148:149], v[156:157]
	v_pk_fma_f32 v[160:161], v[150:151], v[150:151], v[160:161]
	global_load_dwordx4 v[10:13], v166, s[2:3] offset:960
	v_pk_fma_f32 v[152:153], v[14:15], v[76:77], v[152:153] op_sel_hi:[1,0,1] neg_lo:[0,0,1] neg_hi:[0,0,1]
	v_pk_fma_f32 v[154:155], v[16:17], v[76:77], v[154:155] op_sel_hi:[1,0,1] neg_lo:[0,0,1] neg_hi:[0,0,1]
	v_pk_fma_f32 v[174:175], v[152:153], v[152:153], v[174:175]
	v_pk_fma_f32 v[176:177], v[154:155], v[154:155], v[176:177]
	global_load_dwordx4 v[14:17], v166, s[2:3] offset:992
	v_pk_add_f32 v[156:157], v[156:157], v[160:161]
	v_pk_add_f32 v[174:175], v[174:175], v[176:177]
	s_nop 0
	v_pk_add_f32 v[156:157], v[156:157], v[174:175]
	s_nop 0
	v_add_f32_e32 v78, v156, v157
	s_mov_b32 s4, 0x800000
	ds_bpermute_b32 v79, v158, v78
	s_waitcnt lgkmcnt(0)
	v_add_f32_e32 v78, v78, v79
	v_fmamk_f32 v78, v78, 0x3c000000, v185
	v_mul_f32_e32 v79, 0x4b800000, v78
	v_cmp_gt_f32_e32 vcc, s4, v78
	s_nop 1
	v_cndmask_b32_e32 v78, v78, v79, vcc
	v_rsq_f32_e32 v79, v78
	s_nop 1
	v_mul_f32_e32 v90, 0x45800000, v79
	v_cndmask_b32_e32 v90, v79, v90, vcc
	v_mul_f32_e32 v90, 0x3ee34c56, v90
	s_waitcnt vmcnt(14)
	v_permlane32_swap_b32_e32 v188, v190
	v_permlane32_swap_b32_e32 v189, v191
	v_lshlrev_b32_e32 v80, 16, v188
	v_and_b32_e32 v81, 0xffff0000, v188
	v_lshlrev_b32_e32 v82, 16, v189
	v_and_b32_e32 v83, 0xffff0000, v189
	v_pk_mul_f32 v[92:93], v[92:93], v[90:91] op_sel_hi:[1,0]
	v_pk_mul_f32 v[94:95], v[94:95], v[90:91] op_sel_hi:[1,0]
	v_pk_mul_f32 v[92:93], v[50:51], v[92:93]
	v_pk_mul_f32 v[94:95], v[52:53], v[94:95]
	v_pk_mul_f32 v[92:93], v[92:93], v[80:81]
	v_pk_mul_f32 v[94:95], v[94:95], v[82:83]
	v_lshlrev_b32_e32 v84, 16, v190
	v_and_b32_e32 v85, 0xffff0000, v190
	v_lshlrev_b32_e32 v86, 16, v191
	v_and_b32_e32 v87, 0xffff0000, v191
	v_pk_mul_f32 v[96:97], v[96:97], v[90:91] op_sel_hi:[1,0]
	v_pk_mul_f32 v[98:99], v[98:99], v[90:91] op_sel_hi:[1,0]
	v_pk_mul_f32 v[96:97], v[54:55], v[96:97]
	v_pk_mul_f32 v[98:99], v[56:57], v[98:99]
	v_pk_mul_f32 v[96:97], v[96:97], v[84:85]
	v_pk_mul_f32 v[98:99], v[98:99], v[86:87]
	v_cvt_pk_bf16_f32 v92, v92, v93
	v_cvt_pk_bf16_f32 v93, v94, v95
	v_cvt_pk_bf16_f32 v94, v96, v97
	v_cvt_pk_bf16_f32 v95, v98, v99
	s_nop 1
	v_permlane32_swap_b32_e32 v92, v94
	v_permlane32_swap_b32_e32 v93, v95
	global_store_dwordx4 v[88:89], v[92:95], off
	s_waitcnt vmcnt(13)
; #define GAS __attribute__((address_space(1)))
; __device__ __forceinline__ unsigned cvtpk(float lo, float hi) { typedef __bf16 b2 __attribute__((ext_vector_type(2))); f32x2 v = {lo, hi}; b2 b = __builtin_convertvector(v, b2); return __builtin_bit_cast(unsigned, b); }
;     ...
;             for (int d = 0; d < 4; ++d)
; #pragma unroll
;                 for (int rg = 0; rg < 4; ++rg) { const int dc = d * 32 + 8 * rg + 4 * hi; const f32x4 sg = *(const GAS f32x4*)(subg + dc); const v2u gg = *(const GAS v2u*)(GA + dc);
;                     const float y0 = o[d][4 * rg + 0] * rsn * sg[0] * bf_lo(gg.x), y1 = o[d][4 * rg + 1] * rsn * sg[1] * bf_hi(gg.x), y2 = o[d][4 * rg + 2] * rsn * sg[2] * bf_lo(gg.y), y3 = o[d][4 * rg + 3] * rsn * sg[3] * bf_hi(gg.y);
;                     v2u wv; wv.x = cvtpk(y0, y1); wv.y = cvtpk(y2, y3); *(GAS v2u*)(orow + dc) = wv; }
	v_permlane32_swap_b32_e32 v192, v194
	v_permlane32_swap_b32_e32 v193, v195
	v_lshlrev_b32_e32 v80, 16, v192
	v_and_b32_e32 v81, 0xffff0000, v192
	v_lshlrev_b32_e32 v82, 16, v193
	v_and_b32_e32 v83, 0xffff0000, v193
	v_pk_mul_f32 v[100:101], v[100:101], v[90:91] op_sel_hi:[1,0]
	v_pk_mul_f32 v[102:103], v[102:103], v[90:91] op_sel_hi:[1,0]
	v_pk_mul_f32 v[100:101], v[58:59], v[100:101]
	v_pk_mul_f32 v[102:103], v[60:61], v[102:103]
	v_pk_mul_f32 v[100:101], v[100:101], v[80:81]
	v_pk_mul_f32 v[102:103], v[102:103], v[82:83]
	v_lshlrev_b32_e32 v84, 16, v194
	v_and_b32_e32 v85, 0xffff0000, v194
	v_lshlrev_b32_e32 v86, 16, v195
	v_and_b32_e32 v87, 0xffff0000, v195
	v_pk_mul_f32 v[104:105], v[104:105], v[90:91] op_sel_hi:[1,0]
	v_pk_mul_f32 v[106:107], v[106:107], v[90:91] op_sel_hi:[1,0]
	v_pk_mul_f32 v[104:105], v[62:63], v[104:105]
	v_pk_mul_f32 v[106:107], v[64:65], v[106:107]
	v_pk_mul_f32 v[104:105], v[104:105], v[84:85]
	v_pk_mul_f32 v[106:107], v[106:107], v[86:87]
	v_cvt_pk_bf16_f32 v100, v100, v101
	v_cvt_pk_bf16_f32 v101, v102, v103
	v_cvt_pk_bf16_f32 v102, v104, v105
	v_cvt_pk_bf16_f32 v103, v106, v107
	s_nop 1
	v_permlane32_swap_b32_e32 v100, v102
	v_permlane32_swap_b32_e32 v101, v103
	global_store_dwordx4 v[88:89], v[100:103], off offset:32
	s_waitcnt vmcnt(12)
	v_permlane32_swap_b32_e32 v196, v198
	v_permlane32_swap_b32_e32 v197, v199
	v_lshlrev_b32_e32 v80, 16, v196
	v_and_b32_e32 v81, 0xffff0000, v196
	v_lshlrev_b32_e32 v82, 16, v197
	v_and_b32_e32 v83, 0xffff0000, v197
	v_pk_mul_f32 v[108:109], v[108:109], v[90:91] op_sel_hi:[1,0]
	v_pk_mul_f32 v[110:111], v[110:111], v[90:91] op_sel_hi:[1,0]
	v_pk_mul_f32 v[108:109], v[34:35], v[108:109]
	v_pk_mul_f32 v[110:111], v[36:37], v[110:111]
	v_pk_mul_f32 v[108:109], v[108:109], v[80:81]
	v_pk_mul_f32 v[110:111], v[110:111], v[82:83]
	v_lshlrev_b32_e32 v84, 16, v198
	v_and_b32_e32 v85, 0xffff0000, v198
	v_lshlrev_b32_e32 v86, 16, v199
	v_and_b32_e32 v87, 0xffff0000, v199
	v_pk_mul_f32 v[112:113], v[112:113], v[90:91] op_sel_hi:[1,0]
	v_pk_mul_f32 v[114:115], v[114:115], v[90:91] op_sel_hi:[1,0]
	v_pk_mul_f32 v[112:113], v[38:39], v[112:113]
	v_pk_mul_f32 v[114:115], v[40:41], v[114:115]
	v_pk_mul_f32 v[112:113], v[112:113], v[84:85]
	v_pk_mul_f32 v[114:115], v[114:115], v[86:87]
	v_cvt_pk_bf16_f32 v108, v108, v109
	v_cvt_pk_bf16_f32 v109, v110, v111
	v_cvt_pk_bf16_f32 v110, v112, v113
	v_cvt_pk_bf16_f32 v111, v114, v115
	s_nop 1
	v_permlane32_swap_b32_e32 v108, v110
	v_permlane32_swap_b32_e32 v109, v111
	global_store_dwordx4 v[88:89], v[108:111], off offset:64
	s_waitcnt vmcnt(11)
	v_permlane32_swap_b32_e32 v200, v202
	v_permlane32_swap_b32_e32 v201, v203
	v_lshlrev_b32_e32 v80, 16, v200
	v_and_b32_e32 v81, 0xffff0000, v200
	v_lshlrev_b32_e32 v82, 16, v201
	v_and_b32_e32 v83, 0xffff0000, v201
	v_pk_mul_f32 v[116:117], v[116:117], v[90:91] op_sel_hi:[1,0]
	v_pk_mul_f32 v[118:119], v[118:119], v[90:91] op_sel_hi:[1,0]
	v_pk_mul_f32 v[116:117], v[42:43], v[116:117]
	v_pk_mul_f32 v[118:119], v[44:45], v[118:119]
	v_pk_mul_f32 v[116:117], v[116:117], v[80:81]
	v_pk_mul_f32 v[118:119], v[118:119], v[82:83]
	v_lshlrev_b32_e32 v84, 16, v202
	v_and_b32_e32 v85, 0xffff0000, v202
	v_lshlrev_b32_e32 v86, 16, v203
	v_and_b32_e32 v87, 0xffff0000, v203
	v_pk_mul_f32 v[120:121], v[120:121], v[90:91] op_sel_hi:[1,0]
	v_pk_mul_f32 v[122:123], v[122:123], v[90:91] op_sel_hi:[1,0]
	v_pk_mul_f32 v[120:121], v[46:47], v[120:121]
	v_pk_mul_f32 v[122:123], v[48:49], v[122:123]
	v_pk_mul_f32 v[120:121], v[120:121], v[84:85]
	v_pk_mul_f32 v[122:123], v[122:123], v[86:87]
	v_cvt_pk_bf16_f32 v116, v116, v117
	v_cvt_pk_bf16_f32 v117, v118, v119
	v_cvt_pk_bf16_f32 v118, v120, v121
	v_cvt_pk_bf16_f32 v119, v122, v123
	s_nop 1
	v_permlane32_swap_b32_e32 v116, v118
	v_permlane32_swap_b32_e32 v117, v119
	global_store_dwordx4 v[88:89], v[116:119], off offset:96
	s_waitcnt vmcnt(10)
; #define GAS __attribute__((address_space(1)))
; __device__ __forceinline__ unsigned cvtpk(float lo, float hi) { typedef __bf16 b2 __attribute__((ext_vector_type(2))); f32x2 v = {lo, hi}; b2 b = __builtin_convertvector(v, b2); return __builtin_bit_cast(unsigned, b); }
;     ...
;             for (int d = 0; d < 4; ++d)
; #pragma unroll
;                 for (int rg = 0; rg < 4; ++rg) { const int dc = d * 32 + 8 * rg + 4 * hi; const f32x4 sg = *(const GAS f32x4*)(subg + dc); const v2u gg = *(const GAS v2u*)(GA + dc);
;                     const float y0 = o[d][4 * rg + 0] * rsn * sg[0] * bf_lo(gg.x), y1 = o[d][4 * rg + 1] * rsn * sg[1] * bf_hi(gg.x), y2 = o[d][4 * rg + 2] * rsn * sg[2] * bf_lo(gg.y), y3 = o[d][4 * rg + 3] * rsn * sg[3] * bf_hi(gg.y);
;                     v2u wv; wv.x = cvtpk(y0, y1); wv.y = cvtpk(y2, y3); *(GAS v2u*)(orow + dc) = wv; }
	v_permlane32_swap_b32_e32 v204, v206
	v_permlane32_swap_b32_e32 v205, v207
	v_lshlrev_b32_e32 v80, 16, v204
	v_and_b32_e32 v81, 0xffff0000, v204
	v_lshlrev_b32_e32 v82, 16, v205
	v_and_b32_e32 v83, 0xffff0000, v205
	v_pk_mul_f32 v[124:125], v[124:125], v[90:91] op_sel_hi:[1,0]
	v_pk_mul_f32 v[126:127], v[126:127], v[90:91] op_sel_hi:[1,0]
	v_pk_mul_f32 v[124:125], v[18:19], v[124:125]
	v_pk_mul_f32 v[126:127], v[20:21], v[126:127]
	v_pk_mul_f32 v[124:125], v[124:125], v[80:81]
	v_pk_mul_f32 v[126:127], v[126:127], v[82:83]
	v_lshlrev_b32_e32 v84, 16, v206
	v_and_b32_e32 v85, 0xffff0000, v206
	v_lshlrev_b32_e32 v86, 16, v207
	v_and_b32_e32 v87, 0xffff0000, v207
	v_pk_mul_f32 v[128:129], v[128:129], v[90:91] op_sel_hi:[1,0]
	v_pk_mul_f32 v[130:131], v[130:131], v[90:91] op_sel_hi:[1,0]
	v_pk_mul_f32 v[128:129], v[22:23], v[128:129]
	v_pk_mul_f32 v[130:131], v[24:25], v[130:131]
	v_pk_mul_f32 v[128:129], v[128:129], v[84:85]
	v_pk_mul_f32 v[130:131], v[130:131], v[86:87]
	v_cvt_pk_bf16_f32 v124, v124, v125
	v_cvt_pk_bf16_f32 v125, v126, v127
	v_cvt_pk_bf16_f32 v126, v128, v129
	v_cvt_pk_bf16_f32 v127, v130, v131
	s_nop 1
	v_permlane32_swap_b32_e32 v124, v126
	v_permlane32_swap_b32_e32 v125, v127
	global_store_dwordx4 v[88:89], v[124:127], off offset:128
	s_waitcnt vmcnt(9)
	v_permlane32_swap_b32_e32 v208, v210
	v_permlane32_swap_b32_e32 v209, v211
	v_lshlrev_b32_e32 v80, 16, v208
	v_and_b32_e32 v81, 0xffff0000, v208
	v_lshlrev_b32_e32 v82, 16, v209
	v_and_b32_e32 v83, 0xffff0000, v209
	v_pk_mul_f32 v[132:133], v[132:133], v[90:91] op_sel_hi:[1,0]
	v_pk_mul_f32 v[134:135], v[134:135], v[90:91] op_sel_hi:[1,0]
	v_pk_mul_f32 v[132:133], v[26:27], v[132:133]
	v_pk_mul_f32 v[134:135], v[28:29], v[134:135]
	v_pk_mul_f32 v[132:133], v[132:133], v[80:81]
	v_pk_mul_f32 v[134:135], v[134:135], v[82:83]
	v_lshlrev_b32_e32 v84, 16, v210
	v_and_b32_e32 v85, 0xffff0000, v210
	v_lshlrev_b32_e32 v86, 16, v211
	v_and_b32_e32 v87, 0xffff0000, v211
	v_pk_mul_f32 v[136:137], v[136:137], v[90:91] op_sel_hi:[1,0]
	v_pk_mul_f32 v[138:139], v[138:139], v[90:91] op_sel_hi:[1,0]
	v_pk_mul_f32 v[136:137], v[30:31], v[136:137]
	v_pk_mul_f32 v[138:139], v[32:33], v[138:139]
	v_pk_mul_f32 v[136:137], v[136:137], v[84:85]
	v_pk_mul_f32 v[138:139], v[138:139], v[86:87]
	v_cvt_pk_bf16_f32 v132, v132, v133
	v_cvt_pk_bf16_f32 v133, v134, v135
	v_cvt_pk_bf16_f32 v134, v136, v137
	v_cvt_pk_bf16_f32 v135, v138, v139
	s_nop 1
	v_permlane32_swap_b32_e32 v132, v134
	v_permlane32_swap_b32_e32 v133, v135
	global_store_dwordx4 v[88:89], v[132:135], off offset:160
	s_waitcnt vmcnt(8)
	v_permlane32_swap_b32_e32 v212, v214
	v_permlane32_swap_b32_e32 v213, v215
	v_lshlrev_b32_e32 v80, 16, v212
	v_and_b32_e32 v81, 0xffff0000, v212
	v_lshlrev_b32_e32 v82, 16, v213
	v_and_b32_e32 v83, 0xffff0000, v213
	v_pk_mul_f32 v[140:141], v[140:141], v[90:91] op_sel_hi:[1,0]
	v_pk_mul_f32 v[142:143], v[142:143], v[90:91] op_sel_hi:[1,0]
	v_pk_mul_f32 v[140:141], v[2:3], v[140:141]
	v_pk_mul_f32 v[142:143], v[4:5], v[142:143]
	v_pk_mul_f32 v[140:141], v[140:141], v[80:81]
	v_pk_mul_f32 v[142:143], v[142:143], v[82:83]
	v_lshlrev_b32_e32 v84, 16, v214
	v_and_b32_e32 v85, 0xffff0000, v214
	v_lshlrev_b32_e32 v86, 16, v215
	v_and_b32_e32 v87, 0xffff0000, v215
	v_pk_mul_f32 v[144:145], v[144:145], v[90:91] op_sel_hi:[1,0]
	v_pk_mul_f32 v[146:147], v[146:147], v[90:91] op_sel_hi:[1,0]
	v_pk_mul_f32 v[144:145], v[6:7], v[144:145]
	v_pk_mul_f32 v[146:147], v[8:9], v[146:147]
	v_pk_mul_f32 v[144:145], v[144:145], v[84:85]
	v_pk_mul_f32 v[146:147], v[146:147], v[86:87]
	v_cvt_pk_bf16_f32 v140, v140, v141
	v_cvt_pk_bf16_f32 v141, v142, v143
	v_cvt_pk_bf16_f32 v142, v144, v145
	v_cvt_pk_bf16_f32 v143, v146, v147
	s_nop 1
	v_permlane32_swap_b32_e32 v140, v142
	v_permlane32_swap_b32_e32 v141, v143
	global_store_dwordx4 v[88:89], v[140:143], off offset:192
	s_waitcnt vmcnt(7)
	v_permlane32_swap_b32_e32 v216, v218
	v_permlane32_swap_b32_e32 v217, v219
	v_lshlrev_b32_e32 v80, 16, v216
	v_and_b32_e32 v81, 0xffff0000, v216
	v_lshlrev_b32_e32 v82, 16, v217
	v_and_b32_e32 v83, 0xffff0000, v217
	v_pk_mul_f32 v[148:149], v[148:149], v[90:91] op_sel_hi:[1,0]
	v_pk_mul_f32 v[150:151], v[150:151], v[90:91] op_sel_hi:[1,0]
	v_pk_mul_f32 v[148:149], v[10:11], v[148:149]
	v_pk_mul_f32 v[150:151], v[12:13], v[150:151]
	v_pk_mul_f32 v[148:149], v[148:149], v[80:81]
	v_pk_mul_f32 v[150:151], v[150:151], v[82:83]
	v_lshlrev_b32_e32 v84, 16, v218
	v_and_b32_e32 v85, 0xffff0000, v218
	v_lshlrev_b32_e32 v86, 16, v219
	v_and_b32_e32 v87, 0xffff0000, v219
	v_pk_mul_f32 v[152:153], v[152:153], v[90:91] op_sel_hi:[1,0]
	v_pk_mul_f32 v[154:155], v[154:155], v[90:91] op_sel_hi:[1,0]
	v_pk_mul_f32 v[152:153], v[14:15], v[152:153]
	v_pk_mul_f32 v[154:155], v[16:17], v[154:155]
	v_pk_mul_f32 v[152:153], v[152:153], v[84:85]
	v_pk_mul_f32 v[154:155], v[154:155], v[86:87]
	v_cvt_pk_bf16_f32 v148, v148, v149
	v_cvt_pk_bf16_f32 v149, v150, v151
	v_cvt_pk_bf16_f32 v150, v152, v153
	v_cvt_pk_bf16_f32 v151, v154, v155
	s_nop 1
	v_permlane32_swap_b32_e32 v148, v150
	v_permlane32_swap_b32_e32 v149, v151
	global_store_dwordx4 v[88:89], v[148:151], off offset:224
